# v091 with the first gate block's packed epilogue interleaved over all 8 element pairs (4 row tiles) instead of two groups of 4
# speedup vs baseline: 1.0051x; 1.0051x over previous
; #define LAS __attribute__((address_space(3)))
; DI void phase_rglru(const Params& p, unsigned char* shm) {
;     ...
;             {
; #pragma unroll
;                 for (int u = 0; u < 2; ++u) {
;                     if (u == 1 && w >= 4) break;
;                     f32x4 acc[4][2];
; #pragma unroll
;                     for (int mt = 0; mt < 4; ++mt) { acc[mt][0] = (f32x4){0.f, 0.f, 0.f, 0.f}; acc[mt][1] = (f32x4){0.f, 0.f, 0.f, 0.f}; }
; #pragma unroll
;                     for (int kk = 0; kk < 6; ++kk)
; #pragma unroll
;                         for (int mt = 0; mt < 4; ++mt) {
;                             const bf16x8 af = *(const LAS bf16x8*)(lds + XC + (16 * mt + fr) * TR + (32 * kk + 8 * fq) * 2);
;                             acc[mt][0] = __builtin_amdgcn_mfma_f32_16x16x32_bf16(af, Bf[u][kk], acc[mt][0], 0, 0, 0);
;                             acc[mt][1] = __builtin_amdgcn_mfma_f32_16x16x32_bf16(af, Bf[2 + u][kk], acc[mt][1], 0, 0, 0);
;                         }
;                     const int ch = chb + 16 * u + fr;
;                     const float ba = gb[ch], bx = gb[192 + ch], sp = gb[384 + ch];
; #pragma unroll
;                     for (int mt = 0; mt < 4; ++mt)
; #pragma unroll
;                         for (int j = 0; j < 4; ++j) {
;                             const int t = 16 * mt + 4 * fq + j;
;                             const float ea = 1.f + __expf(fminf(-(acc[mt][0][j] + ba), 40.f)), ex = 1.f + __expf(fminf(-(acc[mt][1][j] + bx), 40.f));
;                             const float inv = __builtin_amdgcn_rcpf(ea * ex);
;                             const float r = inv * ex, ig = inv * ea;
;                             const float av = __expf(r * sp), om = 1.f - av;
;                             const float xcv = __uint_as_float((unsigned)*(const LAS bf16_t*)(lds + XC + t * TR + ch * 2) << 16);
.Lconv_x_done:
	s_or_b64 exec, exec, s[2:3]
	s_waitcnt lgkmcnt(0)
	s_barrier
	ds_read_b128 v[120:123], v204 offset:26880
	ds_read_b128 v[124:127], v204 offset:33280
	ds_read_b128 v[128:131], v204 offset:39680
	ds_read_b128 v[132:135], v204 offset:46080
	ds_read_b128 v[226:229], v204 offset:26944
	s_waitcnt lgkmcnt(4)
	v_mfma_f32_16x16x32_bf16 v[148:151], v[120:123], v[0:3], 0
	v_mfma_f32_16x16x32_bf16 v[144:147], v[120:123], v[48:51], 0
	ds_read_b128 v[230:233], v204 offset:33344
	s_waitcnt lgkmcnt(4)
	v_mfma_f32_16x16x32_bf16 v[140:143], v[124:127], v[0:3], 0
	v_mfma_f32_16x16x32_bf16 v[136:139], v[124:127], v[48:51], 0
	ds_read_b128 v[120:123], v204 offset:39744
	s_waitcnt lgkmcnt(4)
	v_mfma_f32_16x16x32_bf16 v[214:217], v[128:131], v[0:3], 0
	v_mfma_f32_16x16x32_bf16 v[210:213], v[128:131], v[48:51], 0
	ds_read_b128 v[124:127], v204 offset:46144
	s_waitcnt lgkmcnt(4)
	v_mfma_f32_16x16x32_bf16 v[218:221], v[132:135], v[0:3], 0
	v_mfma_f32_16x16x32_bf16 v[222:225], v[132:135], v[48:51], 0
	ds_read_b128 v[128:131], v204 offset:27008
	s_waitcnt lgkmcnt(4)
	v_mfma_f32_16x16x32_bf16 v[148:151], v[226:229], v[4:7], v[148:151]
	v_mfma_f32_16x16x32_bf16 v[144:147], v[226:229], v[52:55], v[144:147]
	ds_read_b128 v[132:135], v204 offset:33408
	s_waitcnt lgkmcnt(4)
	v_mfma_f32_16x16x32_bf16 v[140:143], v[230:233], v[4:7], v[140:143]
	v_mfma_f32_16x16x32_bf16 v[136:139], v[230:233], v[52:55], v[136:139]
	ds_read_b128 v[226:229], v204 offset:39808
	s_waitcnt lgkmcnt(4)
	v_mfma_f32_16x16x32_bf16 v[214:217], v[120:123], v[4:7], v[214:217]
	v_mfma_f32_16x16x32_bf16 v[210:213], v[120:123], v[52:55], v[210:213]
	ds_read_b128 v[230:233], v204 offset:46208
	s_waitcnt lgkmcnt(4)
	v_mfma_f32_16x16x32_bf16 v[218:221], v[124:127], v[4:7], v[218:221]
	v_mfma_f32_16x16x32_bf16 v[222:225], v[124:127], v[52:55], v[222:225]
	ds_read_b128 v[120:123], v204 offset:27072
	s_waitcnt lgkmcnt(4)
	v_mfma_f32_16x16x32_bf16 v[148:151], v[128:131], v[8:11], v[148:151]
	v_mfma_f32_16x16x32_bf16 v[144:147], v[128:131], v[56:59], v[144:147]
	ds_read_b128 v[124:127], v204 offset:33472
	s_waitcnt lgkmcnt(4)
	v_mfma_f32_16x16x32_bf16 v[140:143], v[132:135], v[8:11], v[140:143]
	v_mfma_f32_16x16x32_bf16 v[136:139], v[132:135], v[56:59], v[136:139]
	ds_read_b128 v[128:131], v204 offset:39872
	s_waitcnt lgkmcnt(4)
	v_mfma_f32_16x16x32_bf16 v[214:217], v[226:229], v[8:11], v[214:217]
	v_mfma_f32_16x16x32_bf16 v[210:213], v[226:229], v[56:59], v[210:213]
	ds_read_b128 v[132:135], v204 offset:46272
	s_waitcnt lgkmcnt(4)
	v_mfma_f32_16x16x32_bf16 v[218:221], v[230:233], v[8:11], v[218:221]
	v_mfma_f32_16x16x32_bf16 v[222:225], v[230:233], v[56:59], v[222:225]
	ds_read_b128 v[226:229], v204 offset:27136
	s_waitcnt lgkmcnt(4)
	v_mfma_f32_16x16x32_bf16 v[148:151], v[120:123], v[12:15], v[148:151]
	v_mfma_f32_16x16x32_bf16 v[144:147], v[120:123], v[60:63], v[144:147]
	ds_read_b128 v[230:233], v204 offset:33536
	s_waitcnt lgkmcnt(4)
	v_mfma_f32_16x16x32_bf16 v[140:143], v[124:127], v[12:15], v[140:143]
	v_mfma_f32_16x16x32_bf16 v[136:139], v[124:127], v[60:63], v[136:139]
	ds_read_b128 v[120:123], v204 offset:39936
	s_waitcnt lgkmcnt(4)
	v_mfma_f32_16x16x32_bf16 v[214:217], v[128:131], v[12:15], v[214:217]
	v_mfma_f32_16x16x32_bf16 v[210:213], v[128:131], v[60:63], v[210:213]
	ds_read_b128 v[124:127], v204 offset:46336
	s_waitcnt lgkmcnt(4)
	v_mfma_f32_16x16x32_bf16 v[218:221], v[132:135], v[12:15], v[218:221]
	v_mfma_f32_16x16x32_bf16 v[222:225], v[132:135], v[60:63], v[222:225]
	ds_read_b128 v[128:131], v204 offset:27200
	s_waitcnt lgkmcnt(4)
	v_mfma_f32_16x16x32_bf16 v[148:151], v[226:229], v[16:19], v[148:151]
	v_mfma_f32_16x16x32_bf16 v[144:147], v[226:229], v[64:67], v[144:147]
	ds_read_b128 v[132:135], v204 offset:33600
	s_waitcnt lgkmcnt(4)
	v_mfma_f32_16x16x32_bf16 v[140:143], v[230:233], v[16:19], v[140:143]
	v_mfma_f32_16x16x32_bf16 v[136:139], v[230:233], v[64:67], v[136:139]
	s_waitcnt lgkmcnt(3)
	v_mfma_f32_16x16x32_bf16 v[214:217], v[120:123], v[16:19], v[214:217]
	v_mfma_f32_16x16x32_bf16 v[210:213], v[120:123], v[64:67], v[210:213]
	s_waitcnt lgkmcnt(2)
	v_mfma_f32_16x16x32_bf16 v[218:221], v[124:127], v[16:19], v[218:221]
	v_mfma_f32_16x16x32_bf16 v[222:225], v[124:127], v[64:67], v[222:225]
	s_waitcnt lgkmcnt(1)
	v_mfma_f32_16x16x32_bf16 v[148:151], v[128:131], v[20:23], v[148:151]
	v_mfma_f32_16x16x32_bf16 v[144:147], v[128:131], v[68:71], v[144:147]
	s_waitcnt lgkmcnt(0)
	v_mfma_f32_16x16x32_bf16 v[140:143], v[132:135], v[20:23], v[140:143]
	v_mfma_f32_16x16x32_bf16 v[136:139], v[132:135], v[68:71], v[136:139]
	ds_read_b128 v[120:123], v204 offset:40000
	s_nop 1
	ds_read_b128 v[128:131], v204 offset:46400
	ds_read2st64_b32 v[170:171], v184 offset1:3
	ds_read_b32 v205, v184 offset:1536
	ds_read_u16 v226, v194 offset:26880
	ds_read_u16 v227, v194 offset:27280
	ds_read_u16 v228, v194 offset:27680
	ds_read_u16 v229, v194 offset:28080
	ds_read_u16 v230, v194 offset:33280
	ds_read_u16 v231, v194 offset:33680
	ds_read_u16 v232, v194 offset:34080
	ds_read_u16 v233, v194 offset:34480
	ds_read_u16 v234, v194 offset:39680
	ds_read_u16 v235, v194 offset:40080
	ds_read_u16 v236, v194 offset:40480
	ds_read_u16 v237, v194 offset:40880
	ds_read_u16 v238, v194 offset:46080
	ds_read_u16 v239, v194 offset:46480
	ds_read_u16 v240, v194 offset:46880
	ds_read_u16 v241, v194 offset:47280
	s_waitcnt lgkmcnt(15)
; DI void phase_rglru(const Params& p, unsigned char* shm) {
;     ...
;                     const int ch = chb + 16 * u + fr;
;                     const float ba = gb[ch], bx = gb[192 + ch], sp = gb[384 + ch];
; #pragma unroll
;                     for (int mt = 0; mt < 4; ++mt)
; #pragma unroll
;                         for (int j = 0; j < 4; ++j) {
;                             const int t = 16 * mt + 4 * fq + j;
;                             const float ea = 1.f + __expf(fminf(-(acc[mt][0][j] + ba), 40.f)), ex = 1.f + __expf(fminf(-(acc[mt][1][j] + bx), 40.f));
;                             const float inv = __builtin_amdgcn_rcpf(ea * ex);
;                             const float r = inv * ex, ig = inv * ea;
	v_mov_b32_e32 v242, 0xbfb8aa3b
	v_mov_b32_e32 v243, 0x4266d4ca
	v_mul_f32_e32 v170, v242, v170
	v_mul_f32_e32 v171, v242, v171
	v_mul_f32_e32 v205, 0x3fb8aa3b, v205
	v_mfma_f32_16x16x32_bf16 v[124:127], v[120:123], v[20:23], v[214:217]
	v_mfma_f32_16x16x32_bf16 v[120:123], v[120:123], v[68:71], v[210:213]
	v_mfma_f32_16x16x32_bf16 v[132:135], v[128:131], v[20:23], v[218:221]
	v_mfma_f32_16x16x32_bf16 v[128:131], v[128:131], v[68:71], v[222:225]
	v_pk_fma_f32 v[148:149], v[148:149], v[242:243], v[170:171] op_sel_hi:[1,0,0]
	v_pk_fma_f32 v[144:145], v[144:145], v[242:243], v[170:171] op_sel:[0,0,1] op_sel_hi:[1,0,1]
	v_pk_fma_f32 v[150:151], v[150:151], v[242:243], v[170:171] op_sel_hi:[1,0,0]
	v_pk_fma_f32 v[146:147], v[146:147], v[242:243], v[170:171] op_sel:[0,0,1] op_sel_hi:[1,0,1]
	v_pk_fma_f32 v[140:141], v[140:141], v[242:243], v[170:171] op_sel_hi:[1,0,0]
	v_pk_fma_f32 v[136:137], v[136:137], v[242:243], v[170:171] op_sel:[0,0,1] op_sel_hi:[1,0,1]
	v_pk_fma_f32 v[142:143], v[142:143], v[242:243], v[170:171] op_sel_hi:[1,0,0]
	v_pk_fma_f32 v[138:139], v[138:139], v[242:243], v[170:171] op_sel:[0,0,1] op_sel_hi:[1,0,1]
	s_nop 0
	v_pk_fma_f32 v[124:125], v[124:125], v[242:243], v[170:171] op_sel_hi:[1,0,0]
	v_pk_fma_f32 v[120:121], v[120:121], v[242:243], v[170:171] op_sel:[0,0,1] op_sel_hi:[1,0,1]
	v_pk_fma_f32 v[126:127], v[126:127], v[242:243], v[170:171] op_sel_hi:[1,0,0]
	v_pk_fma_f32 v[122:123], v[122:123], v[242:243], v[170:171] op_sel:[0,0,1] op_sel_hi:[1,0,1]
	v_pk_fma_f32 v[132:133], v[132:133], v[242:243], v[170:171] op_sel_hi:[1,0,0]
	v_pk_fma_f32 v[128:129], v[128:129], v[242:243], v[170:171] op_sel:[0,0,1] op_sel_hi:[1,0,1]
	v_pk_fma_f32 v[134:135], v[134:135], v[242:243], v[170:171] op_sel_hi:[1,0,0]
	v_pk_fma_f32 v[130:131], v[130:131], v[242:243], v[170:171] op_sel:[0,0,1] op_sel_hi:[1,0,1]
	v_min_f32_e32 v148, v243, v148
	v_min_f32_e32 v149, v243, v149
	v_min_f32_e32 v144, v243, v144
	v_min_f32_e32 v145, v243, v145
	v_min_f32_e32 v150, v243, v150
	v_min_f32_e32 v151, v243, v151
	v_min_f32_e32 v146, v243, v146
	v_min_f32_e32 v147, v243, v147
	v_min_f32_e32 v140, v243, v140
	v_min_f32_e32 v141, v243, v141
	v_min_f32_e32 v136, v243, v136
	v_min_f32_e32 v137, v243, v137
	v_min_f32_e32 v142, v243, v142
	v_min_f32_e32 v143, v243, v143
	v_min_f32_e32 v138, v243, v138
	v_min_f32_e32 v139, v243, v139
	v_min_f32_e32 v124, v243, v124
	v_min_f32_e32 v125, v243, v125
	v_min_f32_e32 v120, v243, v120
	v_min_f32_e32 v121, v243, v121
	v_min_f32_e32 v126, v243, v126
	v_min_f32_e32 v127, v243, v127
	v_min_f32_e32 v122, v243, v122
	v_min_f32_e32 v123, v243, v123
	v_min_f32_e32 v132, v243, v132
	v_min_f32_e32 v133, v243, v133
	v_min_f32_e32 v128, v243, v128
	v_min_f32_e32 v129, v243, v129
	v_min_f32_e32 v134, v243, v134
	v_min_f32_e32 v135, v243, v135
	v_min_f32_e32 v130, v243, v130
	v_min_f32_e32 v131, v243, v131
	v_exp_f32_e32 v148, v148
	v_exp_f32_e32 v149, v149
	v_exp_f32_e32 v144, v144
	v_exp_f32_e32 v145, v145
	v_exp_f32_e32 v150, v150
	v_exp_f32_e32 v151, v151
	v_exp_f32_e32 v146, v146
	v_exp_f32_e32 v147, v147
	v_exp_f32_e32 v140, v140
	v_exp_f32_e32 v141, v141
	v_exp_f32_e32 v136, v136
	v_exp_f32_e32 v137, v137
	v_exp_f32_e32 v142, v142
	v_exp_f32_e32 v143, v143
	v_exp_f32_e32 v138, v138
	v_exp_f32_e32 v139, v139
	v_exp_f32_e32 v124, v124
	v_exp_f32_e32 v125, v125
	v_exp_f32_e32 v120, v120
	v_exp_f32_e32 v121, v121
	v_exp_f32_e32 v126, v126
	v_exp_f32_e32 v127, v127
	v_exp_f32_e32 v122, v122
	v_exp_f32_e32 v123, v123
	v_exp_f32_e32 v132, v132
	v_exp_f32_e32 v133, v133
	v_exp_f32_e32 v128, v128
	v_exp_f32_e32 v129, v129
	v_exp_f32_e32 v134, v134
	v_exp_f32_e32 v135, v135
	v_exp_f32_e32 v130, v130
	v_exp_f32_e32 v131, v131
	v_pk_add_f32 v[148:149], v[148:149], 1.0 op_sel_hi:[1,0]
	v_pk_add_f32 v[144:145], v[144:145], 1.0 op_sel_hi:[1,0]
	v_pk_add_f32 v[150:151], v[150:151], 1.0 op_sel_hi:[1,0]
	v_pk_add_f32 v[146:147], v[146:147], 1.0 op_sel_hi:[1,0]
	v_pk_add_f32 v[140:141], v[140:141], 1.0 op_sel_hi:[1,0]
	v_pk_add_f32 v[136:137], v[136:137], 1.0 op_sel_hi:[1,0]
	v_pk_add_f32 v[142:143], v[142:143], 1.0 op_sel_hi:[1,0]
	v_pk_add_f32 v[138:139], v[138:139], 1.0 op_sel_hi:[1,0]
	v_pk_add_f32 v[124:125], v[124:125], 1.0 op_sel_hi:[1,0]
	v_pk_add_f32 v[120:121], v[120:121], 1.0 op_sel_hi:[1,0]
	v_pk_add_f32 v[126:127], v[126:127], 1.0 op_sel_hi:[1,0]
	v_pk_add_f32 v[122:123], v[122:123], 1.0 op_sel_hi:[1,0]
	v_pk_add_f32 v[132:133], v[132:133], 1.0 op_sel_hi:[1,0]
	v_pk_add_f32 v[128:129], v[128:129], 1.0 op_sel_hi:[1,0]
	v_pk_add_f32 v[134:135], v[134:135], 1.0 op_sel_hi:[1,0]
	v_pk_add_f32 v[130:131], v[130:131], 1.0 op_sel_hi:[1,0]
	v_pk_mul_f32 v[210:211], v[148:149], v[144:145]
	v_pk_mul_f32 v[212:213], v[150:151], v[146:147]
	v_pk_mul_f32 v[214:215], v[140:141], v[136:137]
	v_pk_mul_f32 v[216:217], v[142:143], v[138:139]
	v_pk_mul_f32 v[218:219], v[124:125], v[120:121]
	v_pk_mul_f32 v[220:221], v[126:127], v[122:123]
	v_pk_mul_f32 v[222:223], v[132:133], v[128:129]
	v_pk_mul_f32 v[224:225], v[134:135], v[130:131]
	v_rcp_f32_e32 v210, v210
	v_rcp_f32_e32 v211, v211
	v_rcp_f32_e32 v212, v212
	v_rcp_f32_e32 v213, v213
	v_rcp_f32_e32 v214, v214
	v_rcp_f32_e32 v215, v215
	v_rcp_f32_e32 v216, v216
	v_rcp_f32_e32 v217, v217
	v_rcp_f32_e32 v218, v218
	v_rcp_f32_e32 v219, v219
	v_rcp_f32_e32 v220, v220
	v_rcp_f32_e32 v221, v221
	v_rcp_f32_e32 v222, v222
	v_rcp_f32_e32 v223, v223
	v_rcp_f32_e32 v224, v224
	v_rcp_f32_e32 v225, v225
	v_pk_mul_f32 v[144:145], v[144:145], v[210:211]
	v_pk_mul_f32 v[148:149], v[148:149], v[210:211]
	v_pk_mul_f32 v[146:147], v[146:147], v[212:213]
	v_pk_mul_f32 v[150:151], v[150:151], v[212:213]
; #define LAS __attribute__((address_space(3)))
; DI void phase_rglru(const Params& p, unsigned char* shm) {
;     ...
;                             const float inv = __builtin_amdgcn_rcpf(ea * ex);
;                             const float r = inv * ex, ig = inv * ea;
;                             const float av = __expf(r * sp), om = 1.f - av;
;                             const float xcv = __uint_as_float((unsigned)*(const LAS bf16_t*)(lds + XC + t * TR + ch * 2) << 16);
;                             const float bt = __builtin_amdgcn_sqrtf(fmaxf(om * (1.f + av), 0.f)) * (ig * xcv);
	v_pk_mul_f32 v[136:137], v[136:137], v[214:215]
	v_pk_mul_f32 v[140:141], v[140:141], v[214:215]
	v_pk_mul_f32 v[138:139], v[138:139], v[216:217]
	v_pk_mul_f32 v[142:143], v[142:143], v[216:217]
	v_pk_mul_f32 v[120:121], v[120:121], v[218:219]
	v_pk_mul_f32 v[124:125], v[124:125], v[218:219]
	v_pk_mul_f32 v[122:123], v[122:123], v[220:221]
	v_pk_mul_f32 v[126:127], v[126:127], v[220:221]
	v_pk_mul_f32 v[128:129], v[128:129], v[222:223]
	v_pk_mul_f32 v[132:133], v[132:133], v[222:223]
	v_pk_mul_f32 v[130:131], v[130:131], v[224:225]
	v_pk_mul_f32 v[134:135], v[134:135], v[224:225]
	v_pk_mul_f32 v[144:145], v[144:145], v[204:205] op_sel:[0,1] op_sel_hi:[1,1]
	v_pk_mul_f32 v[146:147], v[146:147], v[204:205] op_sel:[0,1] op_sel_hi:[1,1]
	v_pk_mul_f32 v[136:137], v[136:137], v[204:205] op_sel:[0,1] op_sel_hi:[1,1]
	v_pk_mul_f32 v[138:139], v[138:139], v[204:205] op_sel:[0,1] op_sel_hi:[1,1]
	v_pk_mul_f32 v[120:121], v[120:121], v[204:205] op_sel:[0,1] op_sel_hi:[1,1]
	v_pk_mul_f32 v[122:123], v[122:123], v[204:205] op_sel:[0,1] op_sel_hi:[1,1]
	v_pk_mul_f32 v[128:129], v[128:129], v[204:205] op_sel:[0,1] op_sel_hi:[1,1]
	v_pk_mul_f32 v[130:131], v[130:131], v[204:205] op_sel:[0,1] op_sel_hi:[1,1]
	v_exp_f32_e32 v144, v144
	v_exp_f32_e32 v145, v145
	v_exp_f32_e32 v146, v146
	v_exp_f32_e32 v147, v147
	v_exp_f32_e32 v136, v136
	v_exp_f32_e32 v137, v137
	v_exp_f32_e32 v138, v138
	v_exp_f32_e32 v139, v139
	v_exp_f32_e32 v120, v120
	v_exp_f32_e32 v121, v121
	v_exp_f32_e32 v122, v122
	v_exp_f32_e32 v123, v123
	v_exp_f32_e32 v128, v128
	v_exp_f32_e32 v129, v129
	v_exp_f32_e32 v130, v130
	v_exp_f32_e32 v131, v131
	v_pk_add_f32 v[210:211], v[144:145], 1.0 op_sel_hi:[1,0] neg_lo:[1,0] neg_hi:[1,0]
	v_pk_add_f32 v[144:145], v[144:145], 1.0 op_sel_hi:[1,0]
	v_pk_add_f32 v[212:213], v[146:147], 1.0 op_sel_hi:[1,0] neg_lo:[1,0] neg_hi:[1,0]
	v_pk_add_f32 v[146:147], v[146:147], 1.0 op_sel_hi:[1,0]
	v_pk_add_f32 v[214:215], v[136:137], 1.0 op_sel_hi:[1,0] neg_lo:[1,0] neg_hi:[1,0]
	v_pk_add_f32 v[136:137], v[136:137], 1.0 op_sel_hi:[1,0]
	v_pk_add_f32 v[216:217], v[138:139], 1.0 op_sel_hi:[1,0] neg_lo:[1,0] neg_hi:[1,0]
	v_pk_add_f32 v[138:139], v[138:139], 1.0 op_sel_hi:[1,0]
	v_pk_add_f32 v[218:219], v[120:121], 1.0 op_sel_hi:[1,0] neg_lo:[1,0] neg_hi:[1,0]
	v_pk_add_f32 v[120:121], v[120:121], 1.0 op_sel_hi:[1,0]
	v_pk_add_f32 v[220:221], v[122:123], 1.0 op_sel_hi:[1,0] neg_lo:[1,0] neg_hi:[1,0]
	v_pk_add_f32 v[122:123], v[122:123], 1.0 op_sel_hi:[1,0]
	v_pk_add_f32 v[222:223], v[128:129], 1.0 op_sel_hi:[1,0] neg_lo:[1,0] neg_hi:[1,0]
	v_pk_add_f32 v[128:129], v[128:129], 1.0 op_sel_hi:[1,0]
	v_pk_add_f32 v[224:225], v[130:131], 1.0 op_sel_hi:[1,0] neg_lo:[1,0] neg_hi:[1,0]
	v_pk_add_f32 v[130:131], v[130:131], 1.0 op_sel_hi:[1,0]
	v_pk_mul_f32 v[144:145], v[210:211], v[144:145]
	v_pk_mul_f32 v[146:147], v[212:213], v[146:147]
	v_pk_mul_f32 v[136:137], v[214:215], v[136:137]
	v_pk_mul_f32 v[138:139], v[216:217], v[138:139]
	v_pk_mul_f32 v[120:121], v[218:219], v[120:121]
	v_pk_mul_f32 v[122:123], v[220:221], v[122:123]
	v_pk_mul_f32 v[128:129], v[222:223], v[128:129]
	v_pk_mul_f32 v[130:131], v[224:225], v[130:131]
	v_max_f32_e32 v144, 0, v144
	v_max_f32_e32 v145, 0, v145
	v_max_f32_e32 v146, 0, v146
	v_max_f32_e32 v147, 0, v147
	v_max_f32_e32 v136, 0, v136
	v_max_f32_e32 v137, 0, v137
	v_max_f32_e32 v138, 0, v138
	v_max_f32_e32 v139, 0, v139
	v_max_f32_e32 v120, 0, v120
	v_max_f32_e32 v121, 0, v121
	v_max_f32_e32 v122, 0, v122
	v_max_f32_e32 v123, 0, v123
	v_max_f32_e32 v128, 0, v128
	v_max_f32_e32 v129, 0, v129
	v_max_f32_e32 v130, 0, v130
	v_max_f32_e32 v131, 0, v131
	v_sqrt_f32_e32 v144, v144
	v_sqrt_f32_e32 v145, v145
	v_sqrt_f32_e32 v146, v146
	v_sqrt_f32_e32 v147, v147
	v_sqrt_f32_e32 v136, v136
	v_sqrt_f32_e32 v137, v137
	v_sqrt_f32_e32 v138, v138
	v_sqrt_f32_e32 v139, v139
	v_sqrt_f32_e32 v120, v120
	v_sqrt_f32_e32 v121, v121
	v_sqrt_f32_e32 v122, v122
	v_sqrt_f32_e32 v123, v123
	v_sqrt_f32_e32 v128, v128
	v_sqrt_f32_e32 v129, v129
	v_sqrt_f32_e32 v130, v130
	v_sqrt_f32_e32 v131, v131
	s_waitcnt lgkmcnt(0)
	v_lshlrev_b32_e32 v226, 16, v226
	v_lshlrev_b32_e32 v227, 16, v227
	v_lshlrev_b32_e32 v228, 16, v228
	v_lshlrev_b32_e32 v229, 16, v229
	v_lshlrev_b32_e32 v230, 16, v230
	v_lshlrev_b32_e32 v231, 16, v231
	v_lshlrev_b32_e32 v232, 16, v232
	v_lshlrev_b32_e32 v233, 16, v233
	v_lshlrev_b32_e32 v234, 16, v234
	v_lshlrev_b32_e32 v235, 16, v235
	v_lshlrev_b32_e32 v236, 16, v236
	v_lshlrev_b32_e32 v237, 16, v237
	v_lshlrev_b32_e32 v238, 16, v238
	v_lshlrev_b32_e32 v239, 16, v239
	v_lshlrev_b32_e32 v240, 16, v240
	v_lshlrev_b32_e32 v241, 16, v241
	v_pk_mul_f32 v[148:149], v[148:149], v[226:227]
	v_pk_mul_f32 v[150:151], v[150:151], v[228:229]
	v_pk_mul_f32 v[140:141], v[140:141], v[230:231]
	v_pk_mul_f32 v[142:143], v[142:143], v[232:233]
	v_pk_mul_f32 v[124:125], v[124:125], v[234:235]
	v_pk_mul_f32 v[126:127], v[126:127], v[236:237]
	v_pk_mul_f32 v[132:133], v[132:133], v[238:239]
	v_pk_mul_f32 v[134:135], v[134:135], v[240:241]
	v_pk_mul_f32 v[148:149], v[148:149], v[144:145]
	v_pk_mul_f32 v[150:151], v[150:151], v[146:147]
	v_pk_mul_f32 v[140:141], v[140:141], v[136:137]
	v_pk_mul_f32 v[142:143], v[142:143], v[138:139]
	v_pk_mul_f32 v[124:125], v[124:125], v[120:121]
	v_pk_mul_f32 v[126:127], v[126:127], v[122:123]
	v_pk_mul_f32 v[132:133], v[132:133], v[128:129]
	v_pk_mul_f32 v[134:135], v[134:135], v[130:131]
	v_cvt_pk_bf16_f32 v210, v210, v211
	v_cvt_pk_bf16_f32 v148, v148, v149
	v_cvt_pk_bf16_f32 v212, v212, v213
	v_cvt_pk_bf16_f32 v150, v150, v151
	v_cvt_pk_bf16_f32 v214, v214, v215
	v_cvt_pk_bf16_f32 v140, v140, v141
	v_cvt_pk_bf16_f32 v216, v216, v217
; #define LAS __attribute__((address_space(3)))
; DI unsigned pk2(float a, float b) { f32x2 v = {a, b}; bf2_t r = __builtin_convertvector(v, bf2_t); return __builtin_bit_cast(unsigned, r); }
; DI void phase_rglru(const Params& p, unsigned char* shm) {
;     ...
;                     for (int kk = 0; kk < 6; ++kk)
; #pragma unroll
;                         for (int mt = 0; mt < 4; ++mt) {
;                             const bf16x8 af = *(const LAS bf16x8*)(lds + XC + (16 * mt + fr) * TR + (32 * kk + 8 * fq) * 2);
;                             acc[mt][0] = __builtin_amdgcn_mfma_f32_16x16x32_bf16(af, Bf[u][kk], acc[mt][0], 0, 0, 0);
;                             acc[mt][1] = __builtin_amdgcn_mfma_f32_16x16x32_bf16(af, Bf[2 + u][kk], acc[mt][1], 0, 0, 0);
;                         }
;                     const int ch = chb + 16 * u + fr;
;                     const float ba = gb[ch], bx = gb[192 + ch], sp = gb[384 + ch];
;     ...
;                             const float ea = 1.f + __expf(fminf(-(acc[mt][0][j] + ba), 40.f)), ex = 1.f + __expf(fminf(-(acc[mt][1][j] + bx), 40.f));
;                             const float inv = __builtin_amdgcn_rcpf(ea * ex);
;                             const float r = inv * ex, ig = inv * ea;
;                             const float av = __expf(r * sp), om = 1.f - av;
;                             const float xcv = __uint_as_float((unsigned)*(const LAS bf16_t*)(lds + XC + t * TR + ch * 2) << 16);
;                             const float bt = __builtin_amdgcn_sqrtf(fmaxf(om * (1.f + av), 0.f)) * (ig * xcv);
;                             *(LAS bf16_t*)(lds + LAo + t * TR + ch * 2) = (bf16_t)(pk2(om, 0.f) & 0xffffu);
;                             *(LAS bf16_t*)(lds + BTo + t * TR + ch * 2) = (bf16_t)(pk2(bt, 0.f) & 0xffffu);
;                         }
	v_cvt_pk_bf16_f32 v142, v142, v143
	v_cvt_pk_bf16_f32 v218, v218, v219
	v_cvt_pk_bf16_f32 v124, v124, v125
	v_cvt_pk_bf16_f32 v220, v220, v221
	v_cvt_pk_bf16_f32 v126, v126, v127
	v_cvt_pk_bf16_f32 v222, v222, v223
	v_cvt_pk_bf16_f32 v132, v132, v133
	v_cvt_pk_bf16_f32 v224, v224, v225
	v_cvt_pk_bf16_f32 v134, v134, v135
	ds_write_b16 v195, v210
	ds_write_b16_d16_hi v195, v210 offset:400
	ds_write_b16 v196, v148
	ds_write_b16_d16_hi v196, v148 offset:400
	ds_write_b16 v195, v212 offset:800
	ds_write_b16_d16_hi v195, v212 offset:1200
	ds_write_b16 v196, v150 offset:800
	ds_write_b16_d16_hi v196, v150 offset:1200
	ds_write_b16 v195, v214 offset:6400
	ds_write_b16_d16_hi v195, v214 offset:6800
	ds_write_b16 v196, v140 offset:6400
	ds_write_b16_d16_hi v196, v140 offset:6800
	ds_write_b16 v195, v216 offset:7200
	ds_write_b16_d16_hi v195, v216 offset:7600
	ds_write_b16 v196, v142 offset:7200
	ds_write_b16_d16_hi v196, v142 offset:7600
	ds_write_b16 v195, v218 offset:12800
	ds_write_b16_d16_hi v195, v218 offset:13200
	ds_write_b16 v196, v124 offset:12800
	ds_write_b16_d16_hi v196, v124 offset:13200
	ds_write_b16 v195, v220 offset:13600
	ds_write_b16_d16_hi v195, v220 offset:14000
	ds_write_b16 v196, v126 offset:13600
	ds_write_b16_d16_hi v196, v126 offset:14000
	ds_write_b16 v195, v222 offset:19200
	ds_write_b16_d16_hi v195, v222 offset:19600
	ds_write_b16 v196, v132 offset:19200
	ds_write_b16_d16_hi v196, v132 offset:19600
	ds_write_b16 v195, v224 offset:20000
	ds_write_b16_d16_hi v195, v224 offset:20400
	ds_write_b16 v196, v134 offset:20000
	ds_write_b16_d16_hi v196, v134 offset:20400
	s_andn2_b64 vcc, exec, s[12:13]
	s_cbranch_vccnz .Lgates_b
	ds_read_b128 v[120:123], v204 offset:26880
	ds_read_b128 v[124:127], v204 offset:33280
	ds_read_b128 v[128:131], v204 offset:26944
	ds_read_b128 v[132:135], v204 offset:33344
	ds_read_b128 v[226:229], v204 offset:27008
	s_waitcnt lgkmcnt(4)
	v_mfma_f32_16x16x32_bf16 v[148:151], v[120:123], v[24:27], 0
	v_mfma_f32_16x16x32_bf16 v[144:147], v[120:123], v[72:75], 0
	ds_read_b128 v[230:233], v204 offset:33408
	s_waitcnt lgkmcnt(4)
	v_mfma_f32_16x16x32_bf16 v[140:143], v[124:127], v[24:27], 0
	v_mfma_f32_16x16x32_bf16 v[136:139], v[124:127], v[72:75], 0
	ds_read_b128 v[120:123], v204 offset:27072
	s_waitcnt lgkmcnt(4)
	v_mfma_f32_16x16x32_bf16 v[148:151], v[128:131], v[28:31], v[148:151]
	v_mfma_f32_16x16x32_bf16 v[144:147], v[128:131], v[76:79], v[144:147]
	ds_read_b128 v[124:127], v204 offset:33472
	s_waitcnt lgkmcnt(4)
	v_mfma_f32_16x16x32_bf16 v[140:143], v[132:135], v[28:31], v[140:143]
	v_mfma_f32_16x16x32_bf16 v[136:139], v[132:135], v[76:79], v[136:139]
	ds_read_b128 v[128:131], v204 offset:27136
	s_waitcnt lgkmcnt(4)
	v_mfma_f32_16x16x32_bf16 v[148:151], v[226:229], v[32:35], v[148:151]
	v_mfma_f32_16x16x32_bf16 v[144:147], v[226:229], v[80:83], v[144:147]
	ds_read_b128 v[132:135], v204 offset:33536
	s_waitcnt lgkmcnt(4)
	v_mfma_f32_16x16x32_bf16 v[140:143], v[230:233], v[32:35], v[140:143]
	v_mfma_f32_16x16x32_bf16 v[136:139], v[230:233], v[80:83], v[136:139]
	ds_read_b128 v[226:229], v204 offset:27200
	s_waitcnt lgkmcnt(4)
	v_mfma_f32_16x16x32_bf16 v[148:151], v[120:123], v[36:39], v[148:151]
	v_mfma_f32_16x16x32_bf16 v[144:147], v[120:123], v[84:87], v[144:147]
	ds_read_b128 v[230:233], v204 offset:33600
	s_waitcnt lgkmcnt(4)
	v_mfma_f32_16x16x32_bf16 v[140:143], v[124:127], v[36:39], v[140:143]
	v_mfma_f32_16x16x32_bf16 v[136:139], v[124:127], v[84:87], v[136:139]
	s_waitcnt lgkmcnt(3)
	v_mfma_f32_16x16x32_bf16 v[148:151], v[128:131], v[40:43], v[148:151]
	v_mfma_f32_16x16x32_bf16 v[144:147], v[128:131], v[88:91], v[144:147]
	s_waitcnt lgkmcnt(2)
	v_mfma_f32_16x16x32_bf16 v[140:143], v[132:135], v[40:43], v[140:143]
	v_mfma_f32_16x16x32_bf16 v[136:139], v[132:135], v[88:91], v[136:139]
	s_waitcnt lgkmcnt(1)
	v_mfma_f32_16x16x32_bf16 v[148:151], v[226:229], v[44:47], v[148:151]
	v_mfma_f32_16x16x32_bf16 v[144:147], v[226:229], v[92:95], v[144:147]
	s_waitcnt lgkmcnt(0)
	v_mfma_f32_16x16x32_bf16 v[140:143], v[230:233], v[44:47], v[140:143]
	v_mfma_f32_16x16x32_bf16 v[136:139], v[230:233], v[92:95], v[136:139]
	s_nop 1
	ds_read2st64_b32 v[170:171], v185 offset1:3
	ds_read_b32 v205, v185 offset:1536
	ds_read_u16 v226, v197 offset:26880
	ds_read_u16 v227, v197 offset:27280
	ds_read_u16 v228, v197 offset:27680
	ds_read_u16 v229, v197 offset:28080
	ds_read_u16 v230, v197 offset:33280
	ds_read_u16 v231, v197 offset:33680
	ds_read_u16 v232, v197 offset:34080
	ds_read_u16 v233, v197 offset:34480
	s_waitcnt lgkmcnt(8)
; #define LAS __attribute__((address_space(3)))
; DI unsigned pk2(float a, float b) { f32x2 v = {a, b}; bf2_t r = __builtin_convertvector(v, bf2_t); return __builtin_bit_cast(unsigned, r); }
; DI void phase_rglru(const Params& p, unsigned char* shm) {
;     ...
;                     const int ch = chb + 16 * u + fr;
;                     const float ba = gb[ch], bx = gb[192 + ch], sp = gb[384 + ch];
; #pragma unroll
;                     for (int mt = 0; mt < 4; ++mt)
; #pragma unroll
;                         for (int j = 0; j < 4; ++j) {
;                             const int t = 16 * mt + 4 * fq + j;
;                             const float ea = 1.f + __expf(fminf(-(acc[mt][0][j] + ba), 40.f)), ex = 1.f + __expf(fminf(-(acc[mt][1][j] + bx), 40.f));
;                             const float inv = __builtin_amdgcn_rcpf(ea * ex);
;                             const float r = inv * ex, ig = inv * ea;
;                             const float av = __expf(r * sp), om = 1.f - av;
;                             const float xcv = __uint_as_float((unsigned)*(const LAS bf16_t*)(lds + XC + t * TR + ch * 2) << 16);
;                             const float bt = __builtin_amdgcn_sqrtf(fmaxf(om * (1.f + av), 0.f)) * (ig * xcv);
;                             *(LAS bf16_t*)(lds + LAo + t * TR + ch * 2) = (bf16_t)(pk2(om, 0.f) & 0xffffu);
;                             *(LAS bf16_t*)(lds + BTo + t * TR + ch * 2) = (bf16_t)(pk2(bt, 0.f) & 0xffffu);
;                         }
	v_mov_b32_e32 v242, 0xbfb8aa3b
	v_mov_b32_e32 v243, 0x4266d4ca
	v_mul_f32_e32 v170, v242, v170
	v_mul_f32_e32 v171, v242, v171
	v_mul_f32_e32 v205, 0x3fb8aa3b, v205
	v_pk_fma_f32 v[148:149], v[148:149], v[242:243], v[170:171] op_sel_hi:[1,0,0]
	v_pk_fma_f32 v[144:145], v[144:145], v[242:243], v[170:171] op_sel:[0,0,1] op_sel_hi:[1,0,1]
	v_pk_fma_f32 v[150:151], v[150:151], v[242:243], v[170:171] op_sel_hi:[1,0,0]
	v_pk_fma_f32 v[146:147], v[146:147], v[242:243], v[170:171] op_sel:[0,0,1] op_sel_hi:[1,0,1]
	v_pk_fma_f32 v[140:141], v[140:141], v[242:243], v[170:171] op_sel_hi:[1,0,0]
	v_pk_fma_f32 v[136:137], v[136:137], v[242:243], v[170:171] op_sel:[0,0,1] op_sel_hi:[1,0,1]
	v_pk_fma_f32 v[142:143], v[142:143], v[242:243], v[170:171] op_sel_hi:[1,0,0]
	v_pk_fma_f32 v[138:139], v[138:139], v[242:243], v[170:171] op_sel:[0,0,1] op_sel_hi:[1,0,1]
	v_min_f32_e32 v148, v243, v148
	v_min_f32_e32 v149, v243, v149
	v_min_f32_e32 v144, v243, v144
	v_min_f32_e32 v145, v243, v145
	v_min_f32_e32 v150, v243, v150
	v_min_f32_e32 v151, v243, v151
	v_min_f32_e32 v146, v243, v146
	v_min_f32_e32 v147, v243, v147
	v_min_f32_e32 v140, v243, v140
	v_min_f32_e32 v141, v243, v141
	v_min_f32_e32 v136, v243, v136
	v_min_f32_e32 v137, v243, v137
	v_min_f32_e32 v142, v243, v142
	v_min_f32_e32 v143, v243, v143
	v_min_f32_e32 v138, v243, v138
	v_min_f32_e32 v139, v243, v139
	v_exp_f32_e32 v148, v148
	v_exp_f32_e32 v149, v149
	v_exp_f32_e32 v144, v144
	v_exp_f32_e32 v145, v145
	v_exp_f32_e32 v150, v150
	v_exp_f32_e32 v151, v151
	v_exp_f32_e32 v146, v146
	v_exp_f32_e32 v147, v147
	v_exp_f32_e32 v140, v140
	v_exp_f32_e32 v141, v141
	v_exp_f32_e32 v136, v136
	v_exp_f32_e32 v137, v137
	v_exp_f32_e32 v142, v142
	v_exp_f32_e32 v143, v143
	v_exp_f32_e32 v138, v138
	v_exp_f32_e32 v139, v139
	v_pk_add_f32 v[148:149], v[148:149], 1.0 op_sel_hi:[1,0]
	v_pk_add_f32 v[144:145], v[144:145], 1.0 op_sel_hi:[1,0]
	v_pk_add_f32 v[150:151], v[150:151], 1.0 op_sel_hi:[1,0]
	v_pk_add_f32 v[146:147], v[146:147], 1.0 op_sel_hi:[1,0]
	v_pk_add_f32 v[140:141], v[140:141], 1.0 op_sel_hi:[1,0]
	v_pk_add_f32 v[136:137], v[136:137], 1.0 op_sel_hi:[1,0]
	v_pk_add_f32 v[142:143], v[142:143], 1.0 op_sel_hi:[1,0]
	v_pk_add_f32 v[138:139], v[138:139], 1.0 op_sel_hi:[1,0]
	v_pk_mul_f32 v[210:211], v[148:149], v[144:145]
	v_pk_mul_f32 v[212:213], v[150:151], v[146:147]
	v_pk_mul_f32 v[214:215], v[140:141], v[136:137]
	v_pk_mul_f32 v[216:217], v[142:143], v[138:139]
	v_rcp_f32_e32 v210, v210
	v_rcp_f32_e32 v211, v211
	v_rcp_f32_e32 v212, v212
	v_rcp_f32_e32 v213, v213
	v_rcp_f32_e32 v214, v214
	v_rcp_f32_e32 v215, v215
	v_rcp_f32_e32 v216, v216
	v_rcp_f32_e32 v217, v217
	v_pk_mul_f32 v[144:145], v[144:145], v[210:211]
	v_pk_mul_f32 v[148:149], v[148:149], v[210:211]
	v_pk_mul_f32 v[146:147], v[146:147], v[212:213]
	v_pk_mul_f32 v[150:151], v[150:151], v[212:213]
	v_pk_mul_f32 v[136:137], v[136:137], v[214:215]
	v_pk_mul_f32 v[140:141], v[140:141], v[214:215]
	v_pk_mul_f32 v[138:139], v[138:139], v[216:217]
	v_pk_mul_f32 v[142:143], v[142:143], v[216:217]
	v_pk_mul_f32 v[144:145], v[144:145], v[204:205] op_sel:[0,1] op_sel_hi:[1,1]
	v_pk_mul_f32 v[146:147], v[146:147], v[204:205] op_sel:[0,1] op_sel_hi:[1,1]
	v_pk_mul_f32 v[136:137], v[136:137], v[204:205] op_sel:[0,1] op_sel_hi:[1,1]
	v_pk_mul_f32 v[138:139], v[138:139], v[204:205] op_sel:[0,1] op_sel_hi:[1,1]
	v_exp_f32_e32 v144, v144
	v_exp_f32_e32 v145, v145
	v_exp_f32_e32 v146, v146
	v_exp_f32_e32 v147, v147
	v_exp_f32_e32 v136, v136
	v_exp_f32_e32 v137, v137
	v_exp_f32_e32 v138, v138
	v_exp_f32_e32 v139, v139
	v_pk_add_f32 v[210:211], v[144:145], 1.0 op_sel_hi:[1,0] neg_lo:[1,0] neg_hi:[1,0]
	v_pk_add_f32 v[144:145], v[144:145], 1.0 op_sel_hi:[1,0]
	v_pk_add_f32 v[212:213], v[146:147], 1.0 op_sel_hi:[1,0] neg_lo:[1,0] neg_hi:[1,0]
	v_pk_add_f32 v[146:147], v[146:147], 1.0 op_sel_hi:[1,0]
	v_pk_add_f32 v[214:215], v[136:137], 1.0 op_sel_hi:[1,0] neg_lo:[1,0] neg_hi:[1,0]
	v_pk_add_f32 v[136:137], v[136:137], 1.0 op_sel_hi:[1,0]
	v_pk_add_f32 v[216:217], v[138:139], 1.0 op_sel_hi:[1,0] neg_lo:[1,0] neg_hi:[1,0]
	v_pk_add_f32 v[138:139], v[138:139], 1.0 op_sel_hi:[1,0]
	v_pk_mul_f32 v[144:145], v[210:211], v[144:145]
	v_pk_mul_f32 v[146:147], v[212:213], v[146:147]
	v_pk_mul_f32 v[136:137], v[214:215], v[136:137]
	v_pk_mul_f32 v[138:139], v[216:217], v[138:139]
	v_max_f32_e32 v144, 0, v144
	v_max_f32_e32 v145, 0, v145
	v_max_f32_e32 v146, 0, v146
	v_max_f32_e32 v147, 0, v147
	v_max_f32_e32 v136, 0, v136
	v_max_f32_e32 v137, 0, v137
	v_max_f32_e32 v138, 0, v138
	v_max_f32_e32 v139, 0, v139
	v_sqrt_f32_e32 v144, v144
	v_sqrt_f32_e32 v145, v145
	v_sqrt_f32_e32 v146, v146
	v_sqrt_f32_e32 v147, v147
	v_sqrt_f32_e32 v136, v136
	v_sqrt_f32_e32 v137, v137
	v_sqrt_f32_e32 v138, v138
	v_sqrt_f32_e32 v139, v139
	s_waitcnt lgkmcnt(0)
	v_lshlrev_b32_e32 v226, 16, v226
	v_lshlrev_b32_e32 v227, 16, v227
	v_lshlrev_b32_e32 v228, 16, v228
	v_lshlrev_b32_e32 v229, 16, v229
	v_lshlrev_b32_e32 v230, 16, v230
	v_lshlrev_b32_e32 v231, 16, v231
	v_lshlrev_b32_e32 v232, 16, v232
	v_lshlrev_b32_e32 v233, 16, v233
	v_pk_mul_f32 v[148:149], v[148:149], v[226:227]
	v_pk_mul_f32 v[150:151], v[150:151], v[228:229]
	v_pk_mul_f32 v[140:141], v[140:141], v[230:231]
	v_pk_mul_f32 v[142:143], v[142:143], v[232:233]
	v_pk_mul_f32 v[148:149], v[148:149], v[144:145]
	v_pk_mul_f32 v[150:151], v[150:151], v[146:147]
	v_pk_mul_f32 v[140:141], v[140:141], v[136:137]
	v_pk_mul_f32 v[142:143], v[142:143], v[138:139]
	v_cvt_pk_bf16_f32 v210, v210, v211
	v_cvt_pk_bf16_f32 v148, v148, v149
	v_cvt_pk_bf16_f32 v212, v212, v213
	v_cvt_pk_bf16_f32 v150, v150, v151
	v_cvt_pk_bf16_f32 v214, v214, v215
	v_cvt_pk_bf16_f32 v140, v140, v141
	v_cvt_pk_bf16_f32 v216, v216, v217
	v_cvt_pk_bf16_f32 v142, v142, v143
	ds_write_b16 v198, v210
	ds_write_b16_d16_hi v198, v210 offset:400
	ds_write_b16 v199, v148
	ds_write_b16_d16_hi v199, v148 offset:400
	ds_write_b16 v198, v212 offset:800
	ds_write_b16_d16_hi v198, v212 offset:1200
	ds_write_b16 v199, v150 offset:800
	ds_write_b16_d16_hi v199, v150 offset:1200
	ds_write_b16 v198, v214 offset:6400
	ds_write_b16_d16_hi v198, v214 offset:6800
	ds_write_b16 v199, v140 offset:6400
	ds_write_b16_d16_hi v199, v140 offset:6800
	ds_write_b16 v198, v216 offset:7200
	ds_write_b16_d16_hi v198, v216 offset:7600
	ds_write_b16 v199, v142 offset:7200
	ds_write_b16_d16_hi v199, v142 offset:7600
	s_branch .LBB0_847
